# NSA selected loop: second half-WG defers PV MFMA block past next step barriers (out-of-phase halves)
# baseline (speedup 1.0000x reference)
; DI f32x4 mfma16(bf16x8 a, bf16x8 b, f32x4 c) { return __builtin_amdgcn_mfma_f32_16x16x32_bf16(a, b, c, 0, 0, 0); }
; template <int MODE, bool FX>
; DI void attn_compute(const int lane, const bf16_t* Ks, const bf16_t* Vs, const bf16x8 (&qf)[2][2], AttnSt& st, const float (&invl)[2],
;                      int lo, int hi, float (&impA)[4], float (&impE)[4], const float CL) {
;     ...
;   if (MODE != 0) {
; #pragma unroll
;     for (int dt = 0; dt < 4; ++dt) {
;       const int row = dt * 16 + col;
;       const int sw = (row >> 1) & 7;
; #pragma unroll
;       for (int c = 0; c < 2; ++c) {
;         uint2 a = *(const uint2*)(Vs + row * 64 + (((4 * c + (quad >> 1)) ^ sw) << 3) + (quad & 1) * 4);
;         uint2 b = *(const uint2*)(Vs + row * 64 + (((4 * c + 2 + (quad >> 1)) ^ sw) << 3) + (quad & 1) * 4);
;         bf16x8 vf = mk8(a.x, a.y, b.x, b.y);
; #pragma unroll
;         for (int hh = 0; hh < 2; ++hh) st.O[hh][dt] = mfma16(vf, pf[hh][c], st.O[hh][dt]);
;       }
;     }
;     if (FX && MODE == 2) {
;       const bf16x8 ones = mk8(0x3F803F80u, 0x3F803F80u, 0x3F803F80u, 0x3F803F80u);
; #pragma unroll
;       for (int c = 0; c < 2; ++c)
; #pragma unroll
;         for (int hh = 0; hh < 2; ++hh) st.L[hh] = mfma16(ones, pf[hh][c], st.L[hh]);
;     }
; template <bool FX>
; DI void nsa_tile(const Params& p, int b, int g, int tile, bf16_t* lds, const float CL) {
;     ...
;         bool sel = (wsel >> (s & 31)) & 1u;
;         int hi = sel ? (tok - s * 64) : -1;
;         if (__any(hi >= 0)) attn_compute<2, FX>(lane, Ks, Vs, qf, st, invl, 0, hi, dA, dE, CL);
.LBB0_666:
	v_cvt_pk_bf16_f32 v82, v164, v165
	v_cvt_pk_bf16_f32 v83, v166, v167
	v_cvt_pk_bf16_f32 v84, v168, v169
	v_cvt_pk_bf16_f32 v85, v170, v171
	v_cvt_pk_bf16_f32 v86, v172, v173
	v_cvt_pk_bf16_f32 v87, v174, v175
	v_cvt_pk_bf16_f32 v88, v176, v177
	v_cvt_pk_bf16_f32 v89, v178, v179
	s_cmp_lg_u32 s101, 0
	s_cbranch_scc0 .Lnsa_pv_now
	s_mov_b32 s100, 1
	s_branch .LBB0_667
.Lnsa_pv_now:
	s_mov_b32 s10, s8
	s_mov_b32 s11, s8
	s_mov_b32 s9, s8
	v_mov_b64_e32 v[92:93], s[10:11]
	v_mov_b64_e32 v[90:91], s[8:9]
	s_waitcnt lgkmcnt(0)
	v_mfma_f32_16x16x32_bf16 v[50:53], v[220:223], v[74:77], v[50:53]
	v_mfma_f32_16x16x32_bf16 v[30:33], v[220:223], v[82:85], v[30:33]
	v_mfma_f32_16x16x32_bf16 v[42:45], v[228:231], v[74:77], v[42:45]
	v_mfma_f32_16x16x32_bf16 v[26:29], v[228:231], v[82:85], v[26:29]
	v_mfma_f32_16x16x32_bf16 v[38:41], v[236:239], v[74:77], v[38:41]
	v_mfma_f32_16x16x32_bf16 v[22:25], v[236:239], v[82:85], v[22:25]
	v_mfma_f32_16x16x32_bf16 v[34:37], v[244:247], v[74:77], v[34:37]
	v_mfma_f32_16x16x32_bf16 v[18:21], v[244:247], v[82:85], v[18:21]
	v_mfma_f32_16x16x32_bf16 v[54:57], v[90:93], v[74:77], v[54:57]
	v_mfma_f32_16x16x32_bf16 v[46:49], v[90:93], v[82:85], v[46:49]
	v_mfma_f32_16x16x32_bf16 v[50:53], v[224:227], v[78:81], v[50:53]
	v_mfma_f32_16x16x32_bf16 v[30:33], v[224:227], v[86:89], v[30:33]
	v_mfma_f32_16x16x32_bf16 v[42:45], v[232:235], v[78:81], v[42:45]
	v_mfma_f32_16x16x32_bf16 v[26:29], v[232:235], v[86:89], v[26:29]
	v_mfma_f32_16x16x32_bf16 v[38:41], v[240:243], v[78:81], v[38:41]
	v_mfma_f32_16x16x32_bf16 v[22:25], v[240:243], v[86:89], v[22:25]
	v_mfma_f32_16x16x32_bf16 v[34:37], v[198:201], v[78:81], v[34:37]
	v_mfma_f32_16x16x32_bf16 v[18:21], v[198:201], v[86:89], v[18:21]
	v_mfma_f32_16x16x32_bf16 v[54:57], v[90:93], v[78:81], v[54:57]
	v_mfma_f32_16x16x32_bf16 v[46:49], v[90:93], v[86:89], v[46:49]

; DI f32x4 mfma16(bf16x8 a, bf16x8 b, f32x4 c) { return __builtin_amdgcn_mfma_f32_16x16x32_bf16(a, b, c, 0, 0, 0); }
; template <int MODE, bool FX>
; DI void attn_compute(const int lane, const bf16_t* Ks, const bf16_t* Vs, const bf16x8 (&qf)[2][2], AttnSt& st, const float (&invl)[2],
;                      int lo, int hi, float (&impA)[4], float (&impE)[4], const float CL) {
;     ...
;   if (MODE != 0) {
; #pragma unroll
;     for (int dt = 0; dt < 4; ++dt) {
;       const int row = dt * 16 + col;
;       const int sw = (row >> 1) & 7;
; #pragma unroll
;       for (int c = 0; c < 2; ++c) {
;         uint2 a = *(const uint2*)(Vs + row * 64 + (((4 * c + (quad >> 1)) ^ sw) << 3) + (quad & 1) * 4);
;         uint2 b = *(const uint2*)(Vs + row * 64 + (((4 * c + 2 + (quad >> 1)) ^ sw) << 3) + (quad & 1) * 4);
;         bf16x8 vf = mk8(a.x, a.y, b.x, b.y);
; #pragma unroll
;         for (int hh = 0; hh < 2; ++hh) st.O[hh][dt] = mfma16(vf, pf[hh][c], st.O[hh][dt]);
;       }
;     }
;     if (FX && MODE == 2) {
;       const bf16x8 ones = mk8(0x3F803F80u, 0x3F803F80u, 0x3F803F80u, 0x3F803F80u);
; #pragma unroll
;       for (int c = 0; c < 2; ++c)
; #pragma unroll
;         for (int hh = 0; hh < 2; ++hh) st.L[hh] = mfma16(ones, pf[hh][c], st.L[hh]);
;     }
; template <bool FX>
; DI void nsa_tile(const Params& p, int b, int g, int tile, bf16_t* lds, const float CL) {
;     ...
;       for (int s = 0; s <= cur; ++s) {
;         __syncthreads();
;         tile64_sstore(tid, Ks, rk0, rk1);
;         tile64_sstore(tid, Vs, rv0, rv1);
;         __syncthreads();
;         if (s < cur) {
;           tile64_gload(tid, rk0, rk1, kb + (size_t)(s + 1) * 64 * ZS, ZS);
;           tile64_gload(tid, rv0, rv1, vsT + (s + 1) * 64, TS);
.LBB0_670:
	s_cmp_eq_u32 s100, 0
	s_cbranch_scc1 .Lnsa_nopend
	s_mov_b32 s10, s8
	s_mov_b32 s11, s8
	s_mov_b32 s9, s8
	v_mov_b64_e32 v[92:93], s[10:11]
	v_mov_b64_e32 v[90:91], s[8:9]
	s_waitcnt lgkmcnt(0)
	v_mfma_f32_16x16x32_bf16 v[50:53], v[220:223], v[74:77], v[50:53]
	v_mfma_f32_16x16x32_bf16 v[30:33], v[220:223], v[82:85], v[30:33]
	v_mfma_f32_16x16x32_bf16 v[42:45], v[228:231], v[74:77], v[42:45]
	v_mfma_f32_16x16x32_bf16 v[26:29], v[228:231], v[82:85], v[26:29]
	v_mfma_f32_16x16x32_bf16 v[38:41], v[236:239], v[74:77], v[38:41]
	v_mfma_f32_16x16x32_bf16 v[22:25], v[236:239], v[82:85], v[22:25]
	v_mfma_f32_16x16x32_bf16 v[34:37], v[244:247], v[74:77], v[34:37]
	v_mfma_f32_16x16x32_bf16 v[18:21], v[244:247], v[82:85], v[18:21]
	v_mfma_f32_16x16x32_bf16 v[54:57], v[90:93], v[74:77], v[54:57]
	v_mfma_f32_16x16x32_bf16 v[46:49], v[90:93], v[82:85], v[46:49]
	v_mfma_f32_16x16x32_bf16 v[50:53], v[224:227], v[78:81], v[50:53]
	v_mfma_f32_16x16x32_bf16 v[30:33], v[224:227], v[86:89], v[30:33]
	v_mfma_f32_16x16x32_bf16 v[42:45], v[232:235], v[78:81], v[42:45]
	v_mfma_f32_16x16x32_bf16 v[26:29], v[232:235], v[86:89], v[26:29]
	v_mfma_f32_16x16x32_bf16 v[38:41], v[240:243], v[78:81], v[38:41]
	v_mfma_f32_16x16x32_bf16 v[22:25], v[240:243], v[86:89], v[22:25]
	v_mfma_f32_16x16x32_bf16 v[34:37], v[198:201], v[78:81], v[34:37]
	v_mfma_f32_16x16x32_bf16 v[18:21], v[198:201], v[86:89], v[18:21]
	v_mfma_f32_16x16x32_bf16 v[54:57], v[90:93], v[78:81], v[54:57]
	v_mfma_f32_16x16x32_bf16 v[46:49], v[90:93], v[86:89], v[46:49]
	s_mov_b32 s100, 0

; DI float bf2f(bf16_t h) { return __uint_as_float(((unsigned)h) << 16); }
; DI float sigmoidf(float x) { return __builtin_amdgcn_rcpf(1.f + __expf(-x)); }
; template <bool FX>
; DI void nsa_tile(const Params& p, int b, int g, int tile, bf16_t* lds, const float CL) {
;     ...
;         if (__any(hi >= 0)) attn_compute<2, FX>(lane, Ks, Vs, qf, st, invl, 0, hi, dA, dE, CL);
;       }
;     }
;     {
;       float sc[2];
; #pragma unroll
;       for (int h = 0; h < 2; ++h) {
;         float l;
;         if (FX) {
;           l = st.L[h][0];
;         } else {
;           l = st.l[h];
;           l += shx(l, 16, lane);
;           l += shx(l, 32, lane);
;         }
;         sc[h] = (l > 0.f) ? sigmoidf(bf2f(ztok[C_GT + 1 * 8 + g * 4 + hp * 2 + h])) / l : 0.f;
;       }
;       nsa_flush<false>(quad, otok + hp * 128, st, sc);
.LBB0_675:
	s_cmp_eq_u32 s100, 0
	s_cbranch_scc1 .Lnsa_noflush
	s_mov_b32 s10, s8
	s_mov_b32 s11, s8
	s_mov_b32 s9, s8
	v_mov_b64_e32 v[92:93], s[10:11]
	v_mov_b64_e32 v[90:91], s[8:9]
	s_waitcnt lgkmcnt(0)
	v_mfma_f32_16x16x32_bf16 v[50:53], v[220:223], v[74:77], v[50:53]
	v_mfma_f32_16x16x32_bf16 v[30:33], v[220:223], v[82:85], v[30:33]
	v_mfma_f32_16x16x32_bf16 v[42:45], v[228:231], v[74:77], v[42:45]
	v_mfma_f32_16x16x32_bf16 v[26:29], v[228:231], v[82:85], v[26:29]
	v_mfma_f32_16x16x32_bf16 v[38:41], v[236:239], v[74:77], v[38:41]
	v_mfma_f32_16x16x32_bf16 v[22:25], v[236:239], v[82:85], v[22:25]
	v_mfma_f32_16x16x32_bf16 v[34:37], v[244:247], v[74:77], v[34:37]
	v_mfma_f32_16x16x32_bf16 v[18:21], v[244:247], v[82:85], v[18:21]
	v_mfma_f32_16x16x32_bf16 v[54:57], v[90:93], v[74:77], v[54:57]
	v_mfma_f32_16x16x32_bf16 v[46:49], v[90:93], v[82:85], v[46:49]
	v_mfma_f32_16x16x32_bf16 v[50:53], v[224:227], v[78:81], v[50:53]
	v_mfma_f32_16x16x32_bf16 v[30:33], v[224:227], v[86:89], v[30:33]
	v_mfma_f32_16x16x32_bf16 v[42:45], v[232:235], v[78:81], v[42:45]
	v_mfma_f32_16x16x32_bf16 v[26:29], v[232:235], v[86:89], v[26:29]
	v_mfma_f32_16x16x32_bf16 v[38:41], v[240:243], v[78:81], v[38:41]
	v_mfma_f32_16x16x32_bf16 v[22:25], v[240:243], v[86:89], v[22:25]
	v_mfma_f32_16x16x32_bf16 v[34:37], v[198:201], v[78:81], v[34:37]
	v_mfma_f32_16x16x32_bf16 v[18:21], v[198:201], v[86:89], v[18:21]
	v_mfma_f32_16x16x32_bf16 v[54:57], v[90:93], v[78:81], v[54:57]
	v_mfma_f32_16x16x32_bf16 v[46:49], v[90:93], v[86:89], v[46:49]
	s_mov_b32 s100, 0
	s_nop 7
	s_nop 7
